# tile placement U: the 200 FFN2 gate/up conversion tiles of the P7 retention WGs moved into the RWKV WGs' end-of-scan slack (WGs 0-127), retention WGs convert none
# baseline (speedup 1.0000x reference)
; __device__ __forceinline__ int fresh_tid(int wv) { int l; asm volatile("v_mbcnt_lo_u32_b32 %0, -1, 0\n\tv_mbcnt_hi_u32_b32 %0, -1, %0" : "=v"(l)); return wv * 64 + l; }
; #define LAS __attribute__((address_space(3)))
; __device__ __forceinline__ void tconv_list(const float* wg, const float* wu, const float* wd, const float* win, const float* wout, unsigned char* ws, const int ntiles, LAS float* t, const int wv) {
;     const int tid = fresh_tid(wv); const int G = gridDim.x;
;     float cur[8], nxt[8];
;     int i = blockIdx.x;
;     if (i < ntiles) { const TDesc d = tconv_desc(wg, wu, wd, win, wout, ws, i);
; #pragma unroll
;         for (int e = 0; e < 8; ++e) { const int idx = e * 512 + tid, r = idx >> 6, c = idx & 63; cur[e] = __builtin_nontemporal_load(d.W + (size_t)(d.k0 + r) * d.N + d.n0 + c); } }
; __global__ void __launch_bounds__(512, 2) hymba_mega(Params P_unused) {
;     ...
;     if (bx < 128) { for (int rw = 0; rw < REP_RW; ++rw) rwkv_unit<false>(P, ldsf, bx >> 4, (bx >> 1) & 7, bx & 1, wv); }
.LBB0_725:
	s_or_b64 exec, exec, s[10:11]
	s_mov_b64 s[38:39], s[0:1]
	s_cmp_lt_u32 s2, 0
	s_cbranch_scc1 .Ltc7_skip
	v_writelane_b32 v40, s4, 4
	v_writelane_b32 v40, s5, 5
	v_writelane_b32 v40, s6, 6
	v_writelane_b32 v40, s7, 7
	v_writelane_b32 v40, s8, 8
	v_writelane_b32 v40, s9, 9
	v_writelane_b32 v40, s10, 10
	v_writelane_b32 v40, s11, 11
	v_writelane_b32 v40, s12, 12
	v_writelane_b32 v40, s13, 13
	v_writelane_b32 v40, s14, 14
	v_writelane_b32 v40, s15, 15
	v_writelane_b32 v40, s16, 16
	v_writelane_b32 v40, s17, 17
	v_writelane_b32 v40, s18, 18
	v_writelane_b32 v40, s19, 19
	v_writelane_b32 v40, s20, 20
	v_writelane_b32 v40, s21, 21
	v_writelane_b32 v40, s22, 22
	v_writelane_b32 v40, s23, 23
	v_writelane_b32 v40, s24, 24
	v_writelane_b32 v40, s25, 25
	v_writelane_b32 v40, s26, 26
	v_writelane_b32 v40, s27, 27
	v_writelane_b32 v40, s28, 28
	v_writelane_b32 v40, s29, 29
	v_writelane_b32 v40, s30, 30
	v_writelane_b32 v40, s31, 31
	s_load_dwordx2 s[24:25], s[38:39], 0xd8
	s_load_dwordx2 s[26:27], s[38:39], 0xd0
	s_load_dwordx2 s[18:19], s[38:39], 0xb8
	s_load_dwordx2 s[20:21], s[38:39], 0xc0
	s_load_dwordx2 s[22:23], s[38:39], 0xc8
	v_mbcnt_lo_u32_b32 v0, -1, 0
	v_mbcnt_hi_u32_b32 v0, -1, v0
	s_lshr_b32 s28, s33, 6
	v_lshlrev_b32_e32 v1, 2, v0
	v_lshrrev_b32_e32 v2, 5, v0
	v_and_b32_e32 v3, 31, v0
	s_mul_i32 s7, s28, 260
	v_add_u32_e32 v5, s7, v1
	v_mul_u32_u24_e32 v6, 0x208, v3
	s_lshl_b32 s7, s28, 3
	v_lshl_add_u32 v6, v2, 2, v6
	v_add_u32_e32 v6, s7, v6
	v_lshlrev_b32_e32 v3, 2, v3
	s_sub_u32 s4, s2, 0
	s_add_u32 s4, s4, 1208
	s_waitcnt lgkmcnt(0)
	s_cmp_lt_u32 s4, 704
	s_cbranch_scc0 .Ltc7_seg1_0
	s_mov_b32 s7, s4
	s_and_b32 s8, s7, 15
	s_lshr_b32 s9, s7, 4
	s_mul_i32 s7, s8, 720896
	s_lshl_b32 s29, s9, 8
	s_add_u32 s7, s7, s29
	s_mul_i32 s29, s28, 11264
	s_add_u32 s7, s7, s29
	s_add_u32 s10, s18, s7
	s_addc_u32 s11, s19, 0
	s_lshr_b32 s7, s9, 1
	s_lshl_b32 s7, s7, 8
	s_and_b32 s29, s9, 1
	s_lshl_b32 s29, s29, 6
	s_add_u32 s7, s7, s29
	s_mul_i32 s7, s7, 2048
	s_lshl_b32 s29, s8, 7
	s_add_u32 s7, s7, s29
	s_mul_i32 s29, s28, 4096
	s_add_u32 s7, s7, s29
	s_add_u32 s12, s26, 0x2100000
	s_addc_u32 s13, s27, 0
	s_add_u32 s12, s12, s7
	s_addc_u32 s13, s13, 0
	s_mov_b32 s14, 90112
	s_mov_b32 s15, 32768
	s_movk_i32 s16, 2048
	s_branch .Ltc7_segend_0
